# P4 scan rewritten as chunked (C=8) f32-MFMA formulation: derive/M/compute stages, swizzled LDS operand layouts
# speedup vs baseline: 1.0676x; 1.0298x over previous
.LBB0_672:
	s_add_i32 s22, s65, 1
	s_and_b32 s23, s65, 1
	s_mul_i32 s24, s23, 0xc000
	v_and_b32_e32 v224, 63, v64
	v_and_b32_e32 v233, 15, v224
	v_lshrrev_b32_e32 v234, 4, v224
	s_mov_b32 s98, 0
	s_mov_b32 s99, -1
	s_cmp_lg_u32 s65, 0
	s_cbranch_scc1 .Lmy_ck_nz
	v_mov_b32_e32 v208, 0
	v_mov_b32_e32 v209, 0
	v_mov_b32_e32 v210, 0
	v_mov_b32_e32 v211, 0
	v_mov_b32_e32 v212, 0
	v_mov_b32_e32 v213, 0
	v_mov_b32_e32 v214, 0
	v_mov_b32_e32 v215, 0
	v_mov_b32_e32 v216, 0
	v_mov_b32_e32 v217, 0
	v_mov_b32_e32 v218, 0
	v_mov_b32_e32 v219, 0
	v_mov_b32_e32 v220, 0
	v_mov_b32_e32 v221, 0
	v_mov_b32_e32 v222, 0
	v_mov_b32_e32 v223, 0
.Lmy_ck_nz:
	v_lshlrev_b32_e32 v236, 4, v224
	v_add_u32_e32 v236, 0x1c000, v236
	v_xor_b32_e32 v225, v224, v234
	v_lshlrev_b32_e32 v225, 4, v225
	v_add_u32_e32 v225, 0x1c000, v225
	v_lshlrev_b32_e32 v226, 4, v234
	v_add_u32_e32 v226, 0x1e000, v226
	v_mov_b32_e32 v72, 0x1e600
	v_cmp_eq_u32_e64 s[96:97], 0, v234
	v_mov_b32_e32 v73, 0x1e500
	v_mov_b32_e32 v74, 0x1e510
	v_cndmask_b32_e64 v227, v72, v73, s[96:97]
	v_cmp_eq_u32_e64 s[96:97], 1, v234
	v_mov_b32_e32 v75, 0x1e590
	v_and_b32_e32 v76, 1, v234
	v_cndmask_b32_e64 v228, v72, v74, s[96:97]
	v_cndmask_b32_e64 v229, v72, v75, s[96:97]
	v_lshlrev_b32_e32 v76, 10, v76
	v_lshl_add_u32 v76, v233, 2, v76
	v_add_u32_e32 v76, s62, v76
	s_add_i32 s96, s24, 0xa000
	v_add_u32_e32 v230, s96, v76
	s_lshl_b32 s96, s23, 13
	s_add_i32 s96, s96, 0x18000
	v_add_u32_e32 v231, s96, v76
	v_add_u32_e32 v232, 48, v224
	v_and_b32_e32 v232, 63, v232
	v_lshlrev_b32_e32 v232, 2, v232
	v_mov_b32_e32 v235, 0
	s_bfe_u32 s96, s62, 0x20006
	s_lshl_b32 s100, s96, 11
	s_add_i32 s100, s100, s24
	v_lshl_add_u32 v72, v224, 2, s100
	s_mul_i32 s97, s96, 0x2700
	s_cmp_gt_u32 s96, 1
	s_cselect_b32 s101, 0x1300, 0
	s_add_i32 s97, s97, s101
	ds_read_b32 v80, v72
	ds_read_b32 v81, v72 offset:256
	ds_read_b32 v82, v72 offset:512
	ds_read_b32 v83, v72 offset:768
	ds_read_b32 v84, v72 offset:1024
	ds_read_b32 v85, v72 offset:1280
	ds_read_b32 v86, v72 offset:1536
	ds_read_b32 v87, v72 offset:1792
	s_cmpk_ge_u32 s62, 0x100
	s_cbranch_scc1 .Lmy_ck_drB
	ds_read_b32 v88, v72 offset:8192
	ds_read_b32 v89, v72 offset:8448
	ds_read_b32 v90, v72 offset:8704
	ds_read_b32 v91, v72 offset:8960
	ds_read_b32 v92, v72 offset:9216
	ds_read_b32 v93, v72 offset:9472
	ds_read_b32 v94, v72 offset:9728
	ds_read_b32 v95, v72 offset:9984
	ds_read_b32 v96, v72 offset:32768
	ds_read_b32 v97, v72 offset:33024
	ds_read_b32 v98, v72 offset:33280
	ds_read_b32 v99, v72 offset:33536
	ds_read_b32 v100, v72 offset:33792
	ds_read_b32 v101, v72 offset:34048
	ds_read_b32 v102, v72 offset:34304
	ds_read_b32 v103, v72 offset:34560
	v_and_b32_e32 v74, 3, v224
	v_bfe_u32 v75, v224, 2, 2
	v_lshrrev_b32_e32 v76, 4, v224
	v_lshlrev_b32_e32 v74, 2, v74
	v_lshl_add_u32 v74, v75, 8, v74
	v_lshl_add_u32 v74, v76, 10, v74
	s_add_i32 s100, s97, 0x1c000
	v_add_u32_e32 v74, s100, v74
	v_xor_b32_e32 v76, 0, v75
	v_xor_b32_e32 v77, 1, v75
	v_xor_b32_e32 v78, 2, v75
	v_xor_b32_e32 v79, 3, v75
	v_lshl_add_u32 v76, v76, 4, v74
	v_lshl_add_u32 v77, v77, 4, v74
	v_lshl_add_u32 v78, v78, 4, v74
	v_lshl_add_u32 v79, v79, 4, v74
	s_waitcnt lgkmcnt(15)
	v_mov_b32_e32 v104, v80
	v_mul_f32_e32 v105, v104, v81
	v_mul_f32_e32 v106, v105, v82
	v_mul_f32_e32 v107, v106, v83
	v_mul_f32_e32 v108, v107, v84
	v_mul_f32_e32 v109, v108, v85
	v_mul_f32_e32 v110, v109, v86
	v_mul_f32_e32 v111, v110, v87
	v_mov_b32_e32 v112, v88
	s_waitcnt lgkmcnt(14)
	v_mul_f32_e32 v113, v104, v89
	s_waitcnt lgkmcnt(13)
	v_mul_f32_e32 v114, v105, v90
	s_waitcnt lgkmcnt(12)
	v_mul_f32_e32 v115, v106, v91
	s_waitcnt lgkmcnt(11)
	v_mul_f32_e32 v116, v107, v92
	s_waitcnt lgkmcnt(10)
	v_mul_f32_e32 v117, v108, v93
	s_waitcnt lgkmcnt(9)
	v_mul_f32_e32 v118, v109, v94
	s_waitcnt lgkmcnt(8)
	v_mul_f32_e32 v119, v110, v95
	s_waitcnt lgkmcnt(7)
	v_mul_f32_e32 v120, v104, v96
	s_waitcnt lgkmcnt(6)
	v_mul_f32_e32 v121, v105, v97
	s_waitcnt lgkmcnt(5)
	v_mul_f32_e32 v122, v106, v98
	s_waitcnt lgkmcnt(4)
	v_mul_f32_e32 v123, v107, v99
	s_waitcnt lgkmcnt(3)
	v_mul_f32_e32 v124, v108, v100
	s_waitcnt lgkmcnt(2)
	v_mul_f32_e32 v125, v109, v101
	s_waitcnt lgkmcnt(1)
	v_mul_f32_e32 v126, v110, v102
	s_waitcnt lgkmcnt(0)
	v_mul_f32_e32 v127, v111, v103
	ds_write_b32 v76, v112
	ds_write_b32 v77, v113
	ds_write_b32 v78, v114
	ds_write_b32 v79, v115
	ds_write_b32 v76, v116 offset:64
	ds_write_b32 v77, v117 offset:64
	ds_write_b32 v78, v118 offset:64
	ds_write_b32 v79, v119 offset:64
	ds_write_b32 v76, v120 offset:128
	ds_write_b32 v77, v121 offset:128
	ds_write_b32 v78, v122 offset:128
	ds_write_b32 v79, v123 offset:128
	ds_write_b32 v76, v124 offset:192
	ds_write_b32 v77, v125 offset:192
	ds_write_b32 v78, v126 offset:192
	ds_write_b32 v79, v127 offset:192
	s_branch .Lmy_ck_drE
.Lmy_ck_drB:
	s_waitcnt lgkmcnt(0)
	ds_read_b32 v88, v72 offset:16384
	ds_read_b32 v89, v72 offset:16640
	ds_read_b32 v90, v72 offset:16896
	ds_read_b32 v91, v72 offset:17152
	ds_read_b32 v92, v72 offset:17408
	ds_read_b32 v93, v72 offset:17664
	ds_read_b32 v94, v72 offset:17920
	ds_read_b32 v95, v72 offset:18176
	ds_read_b32 v96, v72 offset:24576
	ds_read_b32 v97, v72 offset:24832
	ds_read_b32 v98, v72 offset:25088
	ds_read_b32 v99, v72 offset:25344
	ds_read_b32 v100, v72 offset:25600
	ds_read_b32 v101, v72 offset:25856
	ds_read_b32 v102, v72 offset:26112
	ds_read_b32 v103, v72 offset:26368
	v_and_b32_e32 v74, 15, v224
	v_lshrrev_b32_e32 v76, 4, v224
	v_lshlrev_b32_e32 v74, 4, v74
	v_lshl_add_u32 v74, v76, 10, v74
	s_add_i32 s101, s97, 0x1d000
	v_add_u32_e32 v74, s101, v74
	s_add_i32 s101, s97, 0x1e000
	v_lshl_add_u32 v75, v224, 2, s101
	v_mov_b32_e32 v104, v80
	v_mul_f32_e32 v105, v104, v81
	v_mul_f32_e32 v106, v105, v82
	v_mul_f32_e32 v107, v106, v83
	v_mul_f32_e32 v108, v107, v84
	v_mul_f32_e32 v109, v108, v85
	v_mul_f32_e32 v110, v109, v86
	v_mul_f32_e32 v111, v110, v87
	v_rcp_f32_e32 v112, v104
	v_rcp_f32_e32 v113, v105
	v_rcp_f32_e32 v114, v106
	v_rcp_f32_e32 v115, v107
	v_rcp_f32_e32 v116, v108
	v_rcp_f32_e32 v117, v109
	v_rcp_f32_e32 v118, v110
	v_rcp_f32_e32 v119, v111
	s_waitcnt lgkmcnt(7)
	v_mul_f32_e32 v120, v112, v96
	s_waitcnt lgkmcnt(6)
	v_mul_f32_e32 v121, v113, v97
	s_waitcnt lgkmcnt(5)
	v_mul_f32_e32 v122, v114, v98
	s_waitcnt lgkmcnt(4)
	v_mul_f32_e32 v123, v115, v99
	s_waitcnt lgkmcnt(3)
	v_mul_f32_e32 v124, v116, v100
	s_waitcnt lgkmcnt(2)
	v_mul_f32_e32 v125, v117, v101
	s_waitcnt lgkmcnt(1)
	v_mul_f32_e32 v126, v118, v102
	s_waitcnt lgkmcnt(0)
	v_mul_f32_e32 v127, v119, v103
	v_mul_f32_e32 v112, v112, v88
	v_mul_f32_e32 v113, v113, v89
	v_mul_f32_e32 v114, v114, v90
	v_mul_f32_e32 v115, v115, v91
	v_mul_f32_e32 v116, v116, v92
	v_mul_f32_e32 v117, v117, v93
	v_mul_f32_e32 v118, v118, v94
	v_mul_f32_e32 v119, v119, v95
	ds_write_b128 v74, v[112:115]
	ds_write_b128 v74, v[116:119] offset:256
	ds_write_b128 v74, v[120:123] offset:512
	ds_write_b128 v74, v[124:127] offset:768
	ds_write_b32 v75, v111
.Lmy_ck_drE:
	s_waitcnt lgkmcnt(0)
	s_barrier
	s_cmpk_ge_u32 s62, 0x100
	s_cbranch_scc1 .Lmy_ck_mE
	s_lshr_b32 s96, s62, 6
	s_mov_b32 s101, 0x1c000
	s_cmp_gt_u32 s96, 1
	s_cselect_b32 s101, 0x1d300, s101
	s_mul_i32 s96, s96, 0x2700
	s_add_i32 s96, s96, s101
	v_and_b32_e32 v72, 3, v233
	v_lshrrev_b32_e32 v73, 2, v233
	v_lshlrev_b32_e32 v72, 2, v72
	v_lshl_add_u32 v72, v73, 8, v72
	v_lshl_add_u32 v72, v234, 6, v72
	s_add_i32 s97, s96, 0x1000
	v_add_u32_e32 v78, s97, v72
	v_xor_b32_e32 v79, v224, v234
	v_lshl_add_u32 v79, v79, 4, s96
	ds_read_b128 v[96:99], v79
	ds_read_b128 v[100:103], v79 offset:1024
	ds_read_b128 v[104:107], v79 offset:2048
	ds_read_b128 v[108:111], v79 offset:3072
	ds_read_b32 v80, v78
	ds_read_b32 v81, v78 offset:16
	ds_read_b32 v82, v78 offset:32
	ds_read_b32 v83, v78 offset:48
	ds_read_b32 v84, v78 offset:1024
	ds_read_b32 v85, v78 offset:1040
	ds_read_b32 v86, v78 offset:1056
	ds_read_b32 v87, v78 offset:1072
	ds_read_b32 v88, v78 offset:2048
	ds_read_b32 v89, v78 offset:2064
	ds_read_b32 v90, v78 offset:2080
	ds_read_b32 v91, v78 offset:2096
	ds_read_b32 v92, v78 offset:3072
	ds_read_b32 v93, v78 offset:3088
	ds_read_b32 v94, v78 offset:3104
	ds_read_b32 v95, v78 offset:3120
	v_lshl_add_u32 v74, v224, 2, s96
	ds_write_b32 v74, v235 offset:9728
	v_add_u32_e32 v75, -1, v233
	v_mov_b32_e32 v76, -1
	v_cndmask_b32_e64 v75, v76, v75, s[98:99]
	v_cmp_lt_u32_e64 s[100:101], 7, v233
	v_add_u32_e32 v76, -8, v233
	v_and_b32_e32 v77, 1, v234
	v_cndmask_b32_e64 v75, v75, v76, s[100:101]
	v_lshlrev_b32_e32 v77, 2, v77
	v_sub_u32_e32 v76, v75, v77
	v_lshlrev_b32_e32 v77, 2, v234
	v_sub_u32_e32 v77, v233, v77
	v_add_u32_e32 v77, -1, v77
	s_waitcnt lgkmcnt(15)
	v_mfma_f32_16x16x4_f32 v[244:247], v80, v96, 0
	v_mfma_f32_16x16x4_f32 v[240:243], v81, v97, 0
	s_waitcnt lgkmcnt(14)
	v_mfma_f32_16x16x4_f32 v[244:247], v82, v98, v[244:247]
	s_waitcnt lgkmcnt(13)
	v_mfma_f32_16x16x4_f32 v[240:243], v83, v99, v[240:243]
	s_waitcnt lgkmcnt(12)
	v_mfma_f32_16x16x4_f32 v[244:247], v84, v100, v[244:247]
	s_waitcnt lgkmcnt(11)
	v_mfma_f32_16x16x4_f32 v[240:243], v85, v101, v[240:243]
	s_waitcnt lgkmcnt(10)
	v_mfma_f32_16x16x4_f32 v[244:247], v86, v102, v[244:247]
	s_waitcnt lgkmcnt(9)
	v_mfma_f32_16x16x4_f32 v[240:243], v87, v103, v[240:243]
	s_waitcnt lgkmcnt(8)
	v_mfma_f32_16x16x4_f32 v[244:247], v88, v104, v[244:247]
	s_waitcnt lgkmcnt(7)
	v_mfma_f32_16x16x4_f32 v[240:243], v89, v105, v[240:243]
	s_waitcnt lgkmcnt(6)
	v_mfma_f32_16x16x4_f32 v[244:247], v90, v106, v[244:247]
	s_waitcnt lgkmcnt(5)
	v_mfma_f32_16x16x4_f32 v[240:243], v91, v107, v[240:243]
	s_waitcnt lgkmcnt(4)
	v_mfma_f32_16x16x4_f32 v[244:247], v92, v108, v[244:247]
	s_waitcnt lgkmcnt(3)
	v_mfma_f32_16x16x4_f32 v[240:243], v93, v109, v[240:243]
	s_waitcnt lgkmcnt(2)
	v_mfma_f32_16x16x4_f32 v[244:247], v94, v110, v[244:247]
	s_waitcnt lgkmcnt(1)
	v_mfma_f32_16x16x4_f32 v[240:243], v95, v111, v[240:243]
	s_nop 9
	v_add_f32_e32 v244, v244, v240
	v_add_f32_e32 v245, v245, v241
	v_add_f32_e32 v246, v246, v242
	v_add_f32_e32 v247, v247, v243
	v_cmp_le_i32_e64 s[96:97], 0, v76
	v_cmp_le_i32_e64 s[100:101], 1, v76
	s_nop 0
	v_cndmask_b32_e64 v128, 0, v244, s[96:97]
	v_cndmask_b32_e64 v129, 0, v245, s[100:101]
	v_cmp_le_i32_e64 s[96:97], 2, v76
	v_cmp_le_i32_e64 s[100:101], 3, v76
	s_nop 0
	v_cndmask_b32_e64 v130, 0, v246, s[96:97]
	v_cndmask_b32_e64 v131, 0, v247, s[100:101]
	s_lshr_b32 s97, s62, 6
	s_mov_b32 s101, 0x1c000
	s_cmp_gt_u32 s97, 1
	s_cselect_b32 s101, 0x1d300, s101
	s_mul_i32 s97, s97, 0x2700
	s_add_i32 s97, s97, s101
	v_xor_b32_e32 v74, v224, v234
	v_lshl_add_u32 v74, v74, 4, s97
	ds_write_b128 v74, v[128:131] offset:8448
	v_lshlrev_b32_e32 v75, 7, v234
	v_lshl_add_u32 v75, v233, 2, v75
	v_add_u32_e32 v75, s97, v75
	v_cmp_le_i32_e64 s[96:97], 0, v77
	v_cmp_le_i32_e64 s[100:101], 1, v77
	s_nop 0
	v_cndmask_b32_e64 v132, 0, v244, s[96:97]
	v_cndmask_b32_e64 v133, 0, v245, s[100:101]
	v_cmp_le_i32_e64 s[96:97], 2, v77
	v_cmp_le_i32_e64 s[100:101], 3, v77
	s_nop 0
	v_cndmask_b32_e64 v134, 0, v246, s[96:97]
	v_cndmask_b32_e64 v135, 0, v247, s[100:101]
	s_mov_b64 exec, 0x00ff00ff
	ds_write_b32 v75, v132 offset:9472
	ds_write_b32 v75, v133 offset:9504
	ds_write_b32 v75, v134 offset:9536
	ds_write_b32 v75, v135 offset:9568
	s_mov_b64 exec, -1
.Lmy_ck_mE:
	s_waitcnt lgkmcnt(0)
	s_barrier
	s_cmpk_ge_u32 s62, 0x100
	s_cbranch_scc1 .Lmy_ck_cE
	ds_read_b128 v[80:83], v225 offset:8448
	ds_read_b32 v84, v230
	ds_read_b32 v85, v230 offset:256
	ds_read_b32 v86, v230 offset:512
	ds_read_b32 v87, v230 offset:768
	ds_read_b128 v[88:91], v225
	ds_read_b128 v[92:95], v225 offset:1024
	ds_read_b128 v[96:99], v225 offset:2048
	ds_read_b128 v[100:103], v225 offset:3072
	ds_read_b32 v104, v227 offset:4
	ds_read_b32 v105, v227 offset:8
	ds_read_b32 v106, v227 offset:40
	ds_read_b32 v107, v227 offset:12
	ds_read_b32 v108, v227 offset:44
	ds_read_b32 v109, v227 offset:76
	ds_read_b32 v110, v228
	ds_read_b32 v111, v228 offset:32
	ds_read_b32 v112, v228 offset:64
	ds_read_b32 v113, v228 offset:96
	ds_read_b32 v114, v228 offset:4
	ds_read_b32 v115, v228 offset:36
	ds_read_b32 v116, v228 offset:68
	ds_read_b32 v117, v228 offset:100
	ds_read_b32 v118, v228 offset:8
	ds_read_b32 v119, v228 offset:40
	ds_read_b32 v120, v228 offset:72
	ds_read_b32 v121, v228 offset:104
	ds_read_b32 v122, v228 offset:12
	ds_read_b32 v123, v228 offset:44
	ds_read_b32 v124, v228 offset:76
	ds_read_b32 v125, v228 offset:108
	ds_read_b32 v126, v229 offset:4
	ds_read_b32 v127, v229 offset:8
	ds_read_b32 v128, v229 offset:40
	ds_read_b32 v129, v229 offset:12
	ds_read_b32 v130, v229 offset:44
	ds_read_b32 v131, v229 offset:76
	ds_read_b128 v[184:187], v236 offset:4096
	ds_read_b128 v[188:191], v236 offset:5120
	ds_read_b128 v[192:195], v236 offset:6144
	ds_read_b128 v[196:199], v236 offset:7168
	s_waitcnt lgkmcnt(15)
	v_cndmask_b32_e64 v252, 0, v84, s[98:99]
	v_cndmask_b32_e64 v253, 0, v85, s[98:99]
	v_cndmask_b32_e64 v254, 0, v86, s[98:99]
	v_cndmask_b32_e64 v255, 0, v87, s[98:99]
	v_mfma_f32_16x16x4_f32 v[240:243], v80, v252, 0
	v_mfma_f32_16x16x4_f32 v[240:243], v81, v253, v[240:243]
	v_mfma_f32_16x16x4_f32 v[240:243], v82, v254, v[240:243]
	v_mfma_f32_16x16x4_f32 v[240:243], v83, v255, v[240:243]
	v_mfma_f32_16x16x4_f32 v[240:243], v88, v208, v[240:243]
	v_mfma_f32_16x16x4_f32 v[244:247], v89, v209, 0
	v_mfma_f32_16x16x4_f32 v[240:243], v90, v210, v[240:243]
	v_mfma_f32_16x16x4_f32 v[244:247], v91, v211, v[244:247]
	v_mfma_f32_16x16x4_f32 v[240:243], v92, v212, v[240:243]
	v_mfma_f32_16x16x4_f32 v[244:247], v93, v213, v[244:247]
	v_mfma_f32_16x16x4_f32 v[240:243], v94, v214, v[240:243]
	v_mfma_f32_16x16x4_f32 v[244:247], v95, v215, v[244:247]
	v_mfma_f32_16x16x4_f32 v[240:243], v96, v216, v[240:243]
	v_mfma_f32_16x16x4_f32 v[244:247], v97, v217, v[244:247]
	v_mfma_f32_16x16x4_f32 v[240:243], v98, v218, v[240:243]
	v_mfma_f32_16x16x4_f32 v[244:247], v99, v219, v[244:247]
	v_mfma_f32_16x16x4_f32 v[240:243], v100, v220, v[240:243]
	v_mfma_f32_16x16x4_f32 v[244:247], v101, v221, v[244:247]
	v_mfma_f32_16x16x4_f32 v[240:243], v102, v222, v[240:243]
	v_mfma_f32_16x16x4_f32 v[244:247], v103, v223, v[244:247]
	ds_read_b128 v[88:91], v226
	ds_read_b128 v[92:95], v226 offset:64
	ds_read_b128 v[96:99], v226 offset:128
	ds_read_b128 v[100:103], v226 offset:192
	s_nop 5
	v_add_f32_e32 v240, v240, v244
	v_add_f32_e32 v241, v241, v245
	v_add_f32_e32 v242, v242, v246
	v_add_f32_e32 v243, v243, v247
	v_fmac_f32_e32 v241, v104, v240
	v_fmac_f32_e32 v242, v105, v240
	v_fmac_f32_e32 v242, v106, v241
	v_fmac_f32_e32 v243, v107, v240
	v_fmac_f32_e32 v243, v108, v241
	v_fmac_f32_e32 v243, v109, v242
	ds_bpermute_b32 v204, v232, v240
	ds_bpermute_b32 v205, v232, v241
	ds_bpermute_b32 v206, v232, v242
	ds_bpermute_b32 v207, v232, v243
	s_waitcnt lgkmcnt(3)
	v_fmac_f32_e32 v240, v110, v204
	s_waitcnt lgkmcnt(2)
	v_fmac_f32_e32 v240, v111, v205
	s_waitcnt lgkmcnt(1)
	v_fmac_f32_e32 v240, v112, v206
	s_waitcnt lgkmcnt(0)
	v_fmac_f32_e32 v240, v113, v207
	v_fmac_f32_e32 v241, v114, v204
	v_fmac_f32_e32 v241, v115, v205
	v_fmac_f32_e32 v241, v116, v206
	v_fmac_f32_e32 v241, v117, v207
	v_fmac_f32_e32 v242, v118, v204
	v_fmac_f32_e32 v242, v119, v205
	v_fmac_f32_e32 v242, v120, v206
	v_fmac_f32_e32 v242, v121, v207
	v_fmac_f32_e32 v243, v122, v204
	v_fmac_f32_e32 v243, v123, v205
	v_fmac_f32_e32 v243, v124, v206
	v_fmac_f32_e32 v243, v125, v207
	v_fmac_f32_e32 v241, v126, v240
	v_fmac_f32_e32 v242, v127, v240
	v_fmac_f32_e32 v242, v128, v241
	v_fmac_f32_e32 v243, v129, v240
	v_fmac_f32_e32 v243, v130, v241
	v_fmac_f32_e32 v243, v131, v242
	v_cndmask_b32_e64 v200, v240, v84, s[98:99]
	v_cndmask_b32_e64 v201, v241, v85, s[98:99]
	v_cndmask_b32_e64 v202, v242, v86, s[98:99]
	v_cndmask_b32_e64 v203, v243, v87, s[98:99]
	v_cndmask_b32_e64 v252, v240, 0, s[98:99]
	v_cndmask_b32_e64 v253, v241, 0, s[98:99]
	v_cndmask_b32_e64 v254, v242, 0, s[98:99]
	v_cndmask_b32_e64 v255, v243, 0, s[98:99]
	ds_read_b128 v[132:135], v225 offset:18432
	ds_read_b32 v136, v230 offset:2048
	ds_read_b32 v137, v230 offset:2304
	ds_read_b32 v138, v230 offset:2560
	ds_read_b32 v139, v230 offset:2816
	ds_read_b128 v[140:143], v225 offset:9984
	ds_read_b128 v[144:147], v225 offset:11008
	ds_read_b128 v[148:151], v225 offset:12032
	ds_read_b128 v[152:155], v225 offset:13056
	ds_read_b32 v156, v227 offset:9988
	ds_read_b32 v157, v227 offset:9992
	ds_read_b32 v158, v227 offset:10024
	ds_read_b32 v159, v227 offset:9996
	ds_read_b32 v160, v227 offset:10028
	ds_read_b32 v161, v227 offset:10060
	ds_read_b32 v162, v228 offset:9984
	ds_read_b32 v163, v228 offset:10016
	ds_read_b32 v164, v228 offset:10048
	ds_read_b32 v165, v228 offset:10080
	ds_read_b32 v166, v228 offset:9988
	ds_read_b32 v167, v228 offset:10020
	ds_read_b32 v168, v228 offset:10052
	ds_read_b32 v169, v228 offset:10084
	ds_read_b32 v170, v228 offset:9992
	ds_read_b32 v171, v228 offset:10024
	ds_read_b32 v172, v228 offset:10056
	ds_read_b32 v173, v228 offset:10088
	ds_read_b32 v174, v228 offset:9996
	ds_read_b32 v175, v228 offset:10028
	ds_read_b32 v176, v228 offset:10060
	ds_read_b32 v177, v228 offset:10092
	ds_read_b32 v178, v229 offset:9988
	ds_read_b32 v179, v229 offset:9992
	ds_read_b32 v180, v229 offset:10024
	ds_read_b32 v181, v229 offset:9996
	ds_read_b32 v182, v229 offset:10028
	ds_read_b32 v183, v229 offset:10060
	v_mfma_f32_16x16x4_f32 v[208:211], v184, v200, v[208:211]
	v_mfma_f32_16x16x4_f32 v[208:211], v185, v201, v[208:211]
	v_mfma_f32_16x16x4_f32 v[208:211], v186, v202, v[208:211]
	v_mfma_f32_16x16x4_f32 v[208:211], v187, v203, v[208:211]
	v_mfma_f32_16x16x4_f32 v[212:215], v188, v200, v[212:215]
	v_mfma_f32_16x16x4_f32 v[212:215], v189, v201, v[212:215]
	v_mfma_f32_16x16x4_f32 v[212:215], v190, v202, v[212:215]
	v_mfma_f32_16x16x4_f32 v[212:215], v191, v203, v[212:215]
	v_mfma_f32_16x16x4_f32 v[216:219], v192, v200, v[216:219]
	v_mfma_f32_16x16x4_f32 v[216:219], v193, v201, v[216:219]
	v_mfma_f32_16x16x4_f32 v[216:219], v194, v202, v[216:219]
	v_mfma_f32_16x16x4_f32 v[216:219], v195, v203, v[216:219]
	v_mfma_f32_16x16x4_f32 v[220:223], v196, v200, v[220:223]
	v_mfma_f32_16x16x4_f32 v[220:223], v197, v201, v[220:223]
	v_mfma_f32_16x16x4_f32 v[220:223], v198, v202, v[220:223]
	v_mfma_f32_16x16x4_f32 v[220:223], v199, v203, v[220:223]
	v_mfma_f32_16x16x4_f32 v[248:251], v80, v252, v[240:243]
	v_mfma_f32_16x16x4_f32 v[248:251], v81, v253, v[248:251]
	v_mfma_f32_16x16x4_f32 v[248:251], v82, v254, v[248:251]
	v_mfma_f32_16x16x4_f32 v[248:251], v83, v255, v[248:251]
	v_mul_f32_e32 v208, v208, v88
	v_mul_f32_e32 v209, v209, v89
	v_mul_f32_e32 v210, v210, v90
	v_mul_f32_e32 v211, v211, v91
	v_mul_f32_e32 v212, v212, v92
	v_mul_f32_e32 v213, v213, v93
	v_mul_f32_e32 v214, v214, v94
	v_mul_f32_e32 v215, v215, v95
	v_mul_f32_e32 v216, v216, v96
	v_mul_f32_e32 v217, v217, v97
	v_mul_f32_e32 v218, v218, v98
	v_mul_f32_e32 v219, v219, v99
	v_mul_f32_e32 v220, v220, v100
	v_mul_f32_e32 v221, v221, v101
	v_mul_f32_e32 v222, v222, v102
	v_mul_f32_e32 v223, v223, v103
	s_mov_b64 exec, s[98:99]
	ds_write_b32 v231, v248
	ds_write_b32 v231, v249 offset:256
	ds_write_b32 v231, v250 offset:512
	ds_write_b32 v231, v251 offset:768
	s_mov_b64 exec, -1
	ds_read_b128 v[184:187], v236 offset:14080
	ds_read_b128 v[188:191], v236 offset:15104
	ds_read_b128 v[192:195], v236 offset:16128
	ds_read_b128 v[196:199], v236 offset:17152
	s_waitcnt lgkmcnt(15)
	v_cndmask_b32_e64 v252, 0, v136, s[98:99]
	v_cndmask_b32_e64 v253, 0, v137, s[98:99]
	v_cndmask_b32_e64 v254, 0, v138, s[98:99]
	v_cndmask_b32_e64 v255, 0, v139, s[98:99]
	v_mfma_f32_16x16x4_f32 v[240:243], v132, v252, 0
	v_mfma_f32_16x16x4_f32 v[240:243], v133, v253, v[240:243]
	v_mfma_f32_16x16x4_f32 v[240:243], v134, v254, v[240:243]
	v_mfma_f32_16x16x4_f32 v[240:243], v135, v255, v[240:243]
	v_mfma_f32_16x16x4_f32 v[240:243], v140, v208, v[240:243]
	v_mfma_f32_16x16x4_f32 v[244:247], v141, v209, 0
	v_mfma_f32_16x16x4_f32 v[240:243], v142, v210, v[240:243]
	v_mfma_f32_16x16x4_f32 v[244:247], v143, v211, v[244:247]
	v_mfma_f32_16x16x4_f32 v[240:243], v144, v212, v[240:243]
	v_mfma_f32_16x16x4_f32 v[244:247], v145, v213, v[244:247]
	v_mfma_f32_16x16x4_f32 v[240:243], v146, v214, v[240:243]
	v_mfma_f32_16x16x4_f32 v[244:247], v147, v215, v[244:247]
	v_mfma_f32_16x16x4_f32 v[240:243], v148, v216, v[240:243]
	v_mfma_f32_16x16x4_f32 v[244:247], v149, v217, v[244:247]
	v_mfma_f32_16x16x4_f32 v[240:243], v150, v218, v[240:243]
	v_mfma_f32_16x16x4_f32 v[244:247], v151, v219, v[244:247]
	v_mfma_f32_16x16x4_f32 v[240:243], v152, v220, v[240:243]
	v_mfma_f32_16x16x4_f32 v[244:247], v153, v221, v[244:247]
	v_mfma_f32_16x16x4_f32 v[240:243], v154, v222, v[240:243]
	v_mfma_f32_16x16x4_f32 v[244:247], v155, v223, v[244:247]
	ds_read_b128 v[140:143], v226 offset:9984
	ds_read_b128 v[144:147], v226 offset:10048
	ds_read_b128 v[148:151], v226 offset:10112
	ds_read_b128 v[152:155], v226 offset:10176
	s_nop 5
	v_add_f32_e32 v240, v240, v244
	v_add_f32_e32 v241, v241, v245
	v_add_f32_e32 v242, v242, v246
	v_add_f32_e32 v243, v243, v247
	v_fmac_f32_e32 v241, v156, v240
	v_fmac_f32_e32 v242, v157, v240
	v_fmac_f32_e32 v242, v158, v241
	v_fmac_f32_e32 v243, v159, v240
	v_fmac_f32_e32 v243, v160, v241
	v_fmac_f32_e32 v243, v161, v242
	ds_bpermute_b32 v204, v232, v240
	ds_bpermute_b32 v205, v232, v241
	ds_bpermute_b32 v206, v232, v242
	ds_bpermute_b32 v207, v232, v243
	s_waitcnt lgkmcnt(3)
	v_fmac_f32_e32 v240, v162, v204
	s_waitcnt lgkmcnt(2)
	v_fmac_f32_e32 v240, v163, v205
	s_waitcnt lgkmcnt(1)
	v_fmac_f32_e32 v240, v164, v206
	s_waitcnt lgkmcnt(0)
	v_fmac_f32_e32 v240, v165, v207
	v_fmac_f32_e32 v241, v166, v204
	v_fmac_f32_e32 v241, v167, v205
	v_fmac_f32_e32 v241, v168, v206
	v_fmac_f32_e32 v241, v169, v207
	v_fmac_f32_e32 v242, v170, v204
	v_fmac_f32_e32 v242, v171, v205
	v_fmac_f32_e32 v242, v172, v206
	v_fmac_f32_e32 v242, v173, v207
	v_fmac_f32_e32 v243, v174, v204
	v_fmac_f32_e32 v243, v175, v205
	v_fmac_f32_e32 v243, v176, v206
	v_fmac_f32_e32 v243, v177, v207
	v_fmac_f32_e32 v241, v178, v240
	v_fmac_f32_e32 v242, v179, v240
	v_fmac_f32_e32 v242, v180, v241
	v_fmac_f32_e32 v243, v181, v240
	v_fmac_f32_e32 v243, v182, v241
	v_fmac_f32_e32 v243, v183, v242
	v_cndmask_b32_e64 v200, v240, v136, s[98:99]
	v_cndmask_b32_e64 v201, v241, v137, s[98:99]
	v_cndmask_b32_e64 v202, v242, v138, s[98:99]
	v_cndmask_b32_e64 v203, v243, v139, s[98:99]
	v_cndmask_b32_e64 v252, v240, 0, s[98:99]
	v_cndmask_b32_e64 v253, v241, 0, s[98:99]
	v_cndmask_b32_e64 v254, v242, 0, s[98:99]
	v_cndmask_b32_e64 v255, v243, 0, s[98:99]
	ds_read_b128 v[80:83], v225 offset:33280
	ds_read_b32 v84, v230 offset:4096
	ds_read_b32 v85, v230 offset:4352
	ds_read_b32 v86, v230 offset:4608
	ds_read_b32 v87, v230 offset:4864
	ds_read_b128 v[88:91], v225 offset:24832
	ds_read_b128 v[92:95], v225 offset:25856
	ds_read_b128 v[96:99], v225 offset:26880
	ds_read_b128 v[100:103], v225 offset:27904
	ds_read_b32 v104, v227 offset:24836
	ds_read_b32 v105, v227 offset:24840
	ds_read_b32 v106, v227 offset:24872
	ds_read_b32 v107, v227 offset:24844
	ds_read_b32 v108, v227 offset:24876
	ds_read_b32 v109, v227 offset:24908
	ds_read_b32 v110, v228 offset:24832
	ds_read_b32 v111, v228 offset:24864
	ds_read_b32 v112, v228 offset:24896
	ds_read_b32 v113, v228 offset:24928
	ds_read_b32 v114, v228 offset:24836
	ds_read_b32 v115, v228 offset:24868
	ds_read_b32 v116, v228 offset:24900
	ds_read_b32 v117, v228 offset:24932
	ds_read_b32 v118, v228 offset:24840
	ds_read_b32 v119, v228 offset:24872
	ds_read_b32 v120, v228 offset:24904
	ds_read_b32 v121, v228 offset:24936
	ds_read_b32 v122, v228 offset:24844
	ds_read_b32 v123, v228 offset:24876
	ds_read_b32 v124, v228 offset:24908
	ds_read_b32 v125, v228 offset:24940
	ds_read_b32 v126, v229 offset:24836
	ds_read_b32 v127, v229 offset:24840
	ds_read_b32 v128, v229 offset:24872
	ds_read_b32 v129, v229 offset:24844
	ds_read_b32 v130, v229 offset:24876
	ds_read_b32 v131, v229 offset:24908
	v_mfma_f32_16x16x4_f32 v[208:211], v184, v200, v[208:211]
	v_mfma_f32_16x16x4_f32 v[208:211], v185, v201, v[208:211]
	v_mfma_f32_16x16x4_f32 v[208:211], v186, v202, v[208:211]
	v_mfma_f32_16x16x4_f32 v[208:211], v187, v203, v[208:211]
	v_mfma_f32_16x16x4_f32 v[212:215], v188, v200, v[212:215]
	v_mfma_f32_16x16x4_f32 v[212:215], v189, v201, v[212:215]
	v_mfma_f32_16x16x4_f32 v[212:215], v190, v202, v[212:215]
	v_mfma_f32_16x16x4_f32 v[212:215], v191, v203, v[212:215]
	v_mfma_f32_16x16x4_f32 v[216:219], v192, v200, v[216:219]
	v_mfma_f32_16x16x4_f32 v[216:219], v193, v201, v[216:219]
	v_mfma_f32_16x16x4_f32 v[216:219], v194, v202, v[216:219]
	v_mfma_f32_16x16x4_f32 v[216:219], v195, v203, v[216:219]
	v_mfma_f32_16x16x4_f32 v[220:223], v196, v200, v[220:223]
	v_mfma_f32_16x16x4_f32 v[220:223], v197, v201, v[220:223]
	v_mfma_f32_16x16x4_f32 v[220:223], v198, v202, v[220:223]
	v_mfma_f32_16x16x4_f32 v[220:223], v199, v203, v[220:223]
	v_mfma_f32_16x16x4_f32 v[248:251], v132, v252, v[240:243]
	v_mfma_f32_16x16x4_f32 v[248:251], v133, v253, v[248:251]
	v_mfma_f32_16x16x4_f32 v[248:251], v134, v254, v[248:251]
	v_mfma_f32_16x16x4_f32 v[248:251], v135, v255, v[248:251]
	v_mul_f32_e32 v208, v208, v140
	v_mul_f32_e32 v209, v209, v141
	v_mul_f32_e32 v210, v210, v142
	v_mul_f32_e32 v211, v211, v143
	v_mul_f32_e32 v212, v212, v144
	v_mul_f32_e32 v213, v213, v145
	v_mul_f32_e32 v214, v214, v146
	v_mul_f32_e32 v215, v215, v147
	v_mul_f32_e32 v216, v216, v148
	v_mul_f32_e32 v217, v217, v149
	v_mul_f32_e32 v218, v218, v150
	v_mul_f32_e32 v219, v219, v151
	v_mul_f32_e32 v220, v220, v152
	v_mul_f32_e32 v221, v221, v153
	v_mul_f32_e32 v222, v222, v154
	v_mul_f32_e32 v223, v223, v155
	s_mov_b64 exec, s[98:99]
	ds_write_b32 v231, v248 offset:2048
	ds_write_b32 v231, v249 offset:2304
	ds_write_b32 v231, v250 offset:2560
	ds_write_b32 v231, v251 offset:2816
	s_mov_b64 exec, -1
	ds_read_b128 v[184:187], v236 offset:28928
	ds_read_b128 v[188:191], v236 offset:29952
	ds_read_b128 v[192:195], v236 offset:30976
	ds_read_b128 v[196:199], v236 offset:32000
	s_waitcnt lgkmcnt(15)
	v_cndmask_b32_e64 v252, 0, v84, s[98:99]
	v_cndmask_b32_e64 v253, 0, v85, s[98:99]
	v_cndmask_b32_e64 v254, 0, v86, s[98:99]
	v_cndmask_b32_e64 v255, 0, v87, s[98:99]
	v_mfma_f32_16x16x4_f32 v[240:243], v80, v252, 0
	v_mfma_f32_16x16x4_f32 v[240:243], v81, v253, v[240:243]
	v_mfma_f32_16x16x4_f32 v[240:243], v82, v254, v[240:243]
	v_mfma_f32_16x16x4_f32 v[240:243], v83, v255, v[240:243]
	v_mfma_f32_16x16x4_f32 v[240:243], v88, v208, v[240:243]
	v_mfma_f32_16x16x4_f32 v[244:247], v89, v209, 0
	v_mfma_f32_16x16x4_f32 v[240:243], v90, v210, v[240:243]
	v_mfma_f32_16x16x4_f32 v[244:247], v91, v211, v[244:247]
	v_mfma_f32_16x16x4_f32 v[240:243], v92, v212, v[240:243]
	v_mfma_f32_16x16x4_f32 v[244:247], v93, v213, v[244:247]
	v_mfma_f32_16x16x4_f32 v[240:243], v94, v214, v[240:243]
	v_mfma_f32_16x16x4_f32 v[244:247], v95, v215, v[244:247]
	v_mfma_f32_16x16x4_f32 v[240:243], v96, v216, v[240:243]
	v_mfma_f32_16x16x4_f32 v[244:247], v97, v217, v[244:247]
	v_mfma_f32_16x16x4_f32 v[240:243], v98, v218, v[240:243]
	v_mfma_f32_16x16x4_f32 v[244:247], v99, v219, v[244:247]
	v_mfma_f32_16x16x4_f32 v[240:243], v100, v220, v[240:243]
	v_mfma_f32_16x16x4_f32 v[244:247], v101, v221, v[244:247]
	v_mfma_f32_16x16x4_f32 v[240:243], v102, v222, v[240:243]
	v_mfma_f32_16x16x4_f32 v[244:247], v103, v223, v[244:247]
	ds_read_b128 v[88:91], v226 offset:24832
	ds_read_b128 v[92:95], v226 offset:24896
	ds_read_b128 v[96:99], v226 offset:24960
	ds_read_b128 v[100:103], v226 offset:25024
	s_nop 5
	v_add_f32_e32 v240, v240, v244
	v_add_f32_e32 v241, v241, v245
	v_add_f32_e32 v242, v242, v246
	v_add_f32_e32 v243, v243, v247
	v_fmac_f32_e32 v241, v104, v240
	v_fmac_f32_e32 v242, v105, v240
	v_fmac_f32_e32 v242, v106, v241
	v_fmac_f32_e32 v243, v107, v240
	v_fmac_f32_e32 v243, v108, v241
	v_fmac_f32_e32 v243, v109, v242
	ds_bpermute_b32 v204, v232, v240
	ds_bpermute_b32 v205, v232, v241
	ds_bpermute_b32 v206, v232, v242
	ds_bpermute_b32 v207, v232, v243
	s_waitcnt lgkmcnt(3)
	v_fmac_f32_e32 v240, v110, v204
	s_waitcnt lgkmcnt(2)
	v_fmac_f32_e32 v240, v111, v205
	s_waitcnt lgkmcnt(1)
	v_fmac_f32_e32 v240, v112, v206
	s_waitcnt lgkmcnt(0)
	v_fmac_f32_e32 v240, v113, v207
	v_fmac_f32_e32 v241, v114, v204
	v_fmac_f32_e32 v241, v115, v205
	v_fmac_f32_e32 v241, v116, v206
	v_fmac_f32_e32 v241, v117, v207
	v_fmac_f32_e32 v242, v118, v204
	v_fmac_f32_e32 v242, v119, v205
	v_fmac_f32_e32 v242, v120, v206
	v_fmac_f32_e32 v242, v121, v207
	v_fmac_f32_e32 v243, v122, v204
	v_fmac_f32_e32 v243, v123, v205
	v_fmac_f32_e32 v243, v124, v206
	v_fmac_f32_e32 v243, v125, v207
	v_fmac_f32_e32 v241, v126, v240
	v_fmac_f32_e32 v242, v127, v240
	v_fmac_f32_e32 v242, v128, v241
	v_fmac_f32_e32 v243, v129, v240
	v_fmac_f32_e32 v243, v130, v241
	v_fmac_f32_e32 v243, v131, v242
	v_cndmask_b32_e64 v200, v240, v84, s[98:99]
	v_cndmask_b32_e64 v201, v241, v85, s[98:99]
	v_cndmask_b32_e64 v202, v242, v86, s[98:99]
	v_cndmask_b32_e64 v203, v243, v87, s[98:99]
	v_cndmask_b32_e64 v252, v240, 0, s[98:99]
	v_cndmask_b32_e64 v253, v241, 0, s[98:99]
	v_cndmask_b32_e64 v254, v242, 0, s[98:99]
	v_cndmask_b32_e64 v255, v243, 0, s[98:99]
	ds_read_b128 v[132:135], v225 offset:43264
	ds_read_b32 v136, v230 offset:6144
	ds_read_b32 v137, v230 offset:6400
	ds_read_b32 v138, v230 offset:6656
	ds_read_b32 v139, v230 offset:6912
	ds_read_b128 v[140:143], v225 offset:34816
	ds_read_b128 v[144:147], v225 offset:35840
	ds_read_b128 v[148:151], v225 offset:36864
	ds_read_b128 v[152:155], v225 offset:37888
	ds_read_b32 v156, v227 offset:34820
	ds_read_b32 v157, v227 offset:34824
	ds_read_b32 v158, v227 offset:34856
	ds_read_b32 v159, v227 offset:34828
	ds_read_b32 v160, v227 offset:34860
	ds_read_b32 v161, v227 offset:34892
	ds_read_b32 v162, v228 offset:34816
	ds_read_b32 v163, v228 offset:34848
	ds_read_b32 v164, v228 offset:34880
	ds_read_b32 v165, v228 offset:34912
	ds_read_b32 v166, v228 offset:34820
	ds_read_b32 v167, v228 offset:34852
	ds_read_b32 v168, v228 offset:34884
	ds_read_b32 v169, v228 offset:34916
	ds_read_b32 v170, v228 offset:34824
	ds_read_b32 v171, v228 offset:34856
	ds_read_b32 v172, v228 offset:34888
	ds_read_b32 v173, v228 offset:34920
	ds_read_b32 v174, v228 offset:34828
	ds_read_b32 v175, v228 offset:34860
	ds_read_b32 v176, v228 offset:34892
	ds_read_b32 v177, v228 offset:34924
	ds_read_b32 v178, v229 offset:34820
	ds_read_b32 v179, v229 offset:34824
	ds_read_b32 v180, v229 offset:34856
	ds_read_b32 v181, v229 offset:34828
	ds_read_b32 v182, v229 offset:34860
	ds_read_b32 v183, v229 offset:34892
	v_mfma_f32_16x16x4_f32 v[208:211], v184, v200, v[208:211]
	v_mfma_f32_16x16x4_f32 v[208:211], v185, v201, v[208:211]
	v_mfma_f32_16x16x4_f32 v[208:211], v186, v202, v[208:211]
	v_mfma_f32_16x16x4_f32 v[208:211], v187, v203, v[208:211]
	v_mfma_f32_16x16x4_f32 v[212:215], v188, v200, v[212:215]
	v_mfma_f32_16x16x4_f32 v[212:215], v189, v201, v[212:215]
	v_mfma_f32_16x16x4_f32 v[212:215], v190, v202, v[212:215]
	v_mfma_f32_16x16x4_f32 v[212:215], v191, v203, v[212:215]
	v_mfma_f32_16x16x4_f32 v[216:219], v192, v200, v[216:219]
	v_mfma_f32_16x16x4_f32 v[216:219], v193, v201, v[216:219]
	v_mfma_f32_16x16x4_f32 v[216:219], v194, v202, v[216:219]
	v_mfma_f32_16x16x4_f32 v[216:219], v195, v203, v[216:219]
	v_mfma_f32_16x16x4_f32 v[220:223], v196, v200, v[220:223]
	v_mfma_f32_16x16x4_f32 v[220:223], v197, v201, v[220:223]
	v_mfma_f32_16x16x4_f32 v[220:223], v198, v202, v[220:223]
	v_mfma_f32_16x16x4_f32 v[220:223], v199, v203, v[220:223]
	v_mfma_f32_16x16x4_f32 v[248:251], v80, v252, v[240:243]
	v_mfma_f32_16x16x4_f32 v[248:251], v81, v253, v[248:251]
	v_mfma_f32_16x16x4_f32 v[248:251], v82, v254, v[248:251]
	v_mfma_f32_16x16x4_f32 v[248:251], v83, v255, v[248:251]
	v_mul_f32_e32 v208, v208, v88
	v_mul_f32_e32 v209, v209, v89
	v_mul_f32_e32 v210, v210, v90
	v_mul_f32_e32 v211, v211, v91
	v_mul_f32_e32 v212, v212, v92
	v_mul_f32_e32 v213, v213, v93
	v_mul_f32_e32 v214, v214, v94
	v_mul_f32_e32 v215, v215, v95
	v_mul_f32_e32 v216, v216, v96
	v_mul_f32_e32 v217, v217, v97
	v_mul_f32_e32 v218, v218, v98
	v_mul_f32_e32 v219, v219, v99
	v_mul_f32_e32 v220, v220, v100
	v_mul_f32_e32 v221, v221, v101
	v_mul_f32_e32 v222, v222, v102
	v_mul_f32_e32 v223, v223, v103
	s_mov_b64 exec, s[98:99]
	ds_write_b32 v231, v248 offset:4096
	ds_write_b32 v231, v249 offset:4352
	ds_write_b32 v231, v250 offset:4608
	ds_write_b32 v231, v251 offset:4864
	s_mov_b64 exec, -1
	ds_read_b128 v[184:187], v236 offset:38912
	ds_read_b128 v[188:191], v236 offset:39936
	ds_read_b128 v[192:195], v236 offset:40960
	ds_read_b128 v[196:199], v236 offset:41984
	s_waitcnt lgkmcnt(15)
	v_cndmask_b32_e64 v252, 0, v136, s[98:99]
	v_cndmask_b32_e64 v253, 0, v137, s[98:99]
	v_cndmask_b32_e64 v254, 0, v138, s[98:99]
	v_cndmask_b32_e64 v255, 0, v139, s[98:99]
	v_mfma_f32_16x16x4_f32 v[240:243], v132, v252, 0
	v_mfma_f32_16x16x4_f32 v[240:243], v133, v253, v[240:243]
	v_mfma_f32_16x16x4_f32 v[240:243], v134, v254, v[240:243]
	v_mfma_f32_16x16x4_f32 v[240:243], v135, v255, v[240:243]
	v_mfma_f32_16x16x4_f32 v[240:243], v140, v208, v[240:243]
	v_mfma_f32_16x16x4_f32 v[244:247], v141, v209, 0
	v_mfma_f32_16x16x4_f32 v[240:243], v142, v210, v[240:243]
	v_mfma_f32_16x16x4_f32 v[244:247], v143, v211, v[244:247]
	v_mfma_f32_16x16x4_f32 v[240:243], v144, v212, v[240:243]
	v_mfma_f32_16x16x4_f32 v[244:247], v145, v213, v[244:247]
	v_mfma_f32_16x16x4_f32 v[240:243], v146, v214, v[240:243]
	v_mfma_f32_16x16x4_f32 v[244:247], v147, v215, v[244:247]
	v_mfma_f32_16x16x4_f32 v[240:243], v148, v216, v[240:243]
	v_mfma_f32_16x16x4_f32 v[244:247], v149, v217, v[244:247]
	v_mfma_f32_16x16x4_f32 v[240:243], v150, v218, v[240:243]
	v_mfma_f32_16x16x4_f32 v[244:247], v151, v219, v[244:247]
	v_mfma_f32_16x16x4_f32 v[240:243], v152, v220, v[240:243]
	v_mfma_f32_16x16x4_f32 v[244:247], v153, v221, v[244:247]
	v_mfma_f32_16x16x4_f32 v[240:243], v154, v222, v[240:243]
	v_mfma_f32_16x16x4_f32 v[244:247], v155, v223, v[244:247]
	ds_read_b128 v[140:143], v226 offset:34816
	ds_read_b128 v[144:147], v226 offset:34880
	ds_read_b128 v[148:151], v226 offset:34944
	ds_read_b128 v[152:155], v226 offset:35008
	s_nop 5
	v_add_f32_e32 v240, v240, v244
	v_add_f32_e32 v241, v241, v245
	v_add_f32_e32 v242, v242, v246
	v_add_f32_e32 v243, v243, v247
	v_fmac_f32_e32 v241, v156, v240
	v_fmac_f32_e32 v242, v157, v240
	v_fmac_f32_e32 v242, v158, v241
	v_fmac_f32_e32 v243, v159, v240
	v_fmac_f32_e32 v243, v160, v241
	v_fmac_f32_e32 v243, v161, v242
	ds_bpermute_b32 v204, v232, v240
	ds_bpermute_b32 v205, v232, v241
	ds_bpermute_b32 v206, v232, v242
	ds_bpermute_b32 v207, v232, v243
	s_waitcnt lgkmcnt(3)
	v_fmac_f32_e32 v240, v162, v204
	s_waitcnt lgkmcnt(2)
	v_fmac_f32_e32 v240, v163, v205
	s_waitcnt lgkmcnt(1)
	v_fmac_f32_e32 v240, v164, v206
	s_waitcnt lgkmcnt(0)
	v_fmac_f32_e32 v240, v165, v207
	v_fmac_f32_e32 v241, v166, v204
	v_fmac_f32_e32 v241, v167, v205
	v_fmac_f32_e32 v241, v168, v206
	v_fmac_f32_e32 v241, v169, v207
	v_fmac_f32_e32 v242, v170, v204
	v_fmac_f32_e32 v242, v171, v205
	v_fmac_f32_e32 v242, v172, v206
	v_fmac_f32_e32 v242, v173, v207
	v_fmac_f32_e32 v243, v174, v204
	v_fmac_f32_e32 v243, v175, v205
	v_fmac_f32_e32 v243, v176, v206
	v_fmac_f32_e32 v243, v177, v207
	v_fmac_f32_e32 v241, v178, v240
	v_fmac_f32_e32 v242, v179, v240
	v_fmac_f32_e32 v242, v180, v241
	v_fmac_f32_e32 v243, v181, v240
	v_fmac_f32_e32 v243, v182, v241
	v_fmac_f32_e32 v243, v183, v242
	v_cndmask_b32_e64 v200, v240, v136, s[98:99]
	v_cndmask_b32_e64 v201, v241, v137, s[98:99]
	v_cndmask_b32_e64 v202, v242, v138, s[98:99]
	v_cndmask_b32_e64 v203, v243, v139, s[98:99]
	v_cndmask_b32_e64 v252, v240, 0, s[98:99]
	v_cndmask_b32_e64 v253, v241, 0, s[98:99]
	v_cndmask_b32_e64 v254, v242, 0, s[98:99]
	v_cndmask_b32_e64 v255, v243, 0, s[98:99]
	v_mfma_f32_16x16x4_f32 v[208:211], v184, v200, v[208:211]
	v_mfma_f32_16x16x4_f32 v[208:211], v185, v201, v[208:211]
	v_mfma_f32_16x16x4_f32 v[208:211], v186, v202, v[208:211]
	v_mfma_f32_16x16x4_f32 v[208:211], v187, v203, v[208:211]
	v_mfma_f32_16x16x4_f32 v[212:215], v188, v200, v[212:215]
	v_mfma_f32_16x16x4_f32 v[212:215], v189, v201, v[212:215]
	v_mfma_f32_16x16x4_f32 v[212:215], v190, v202, v[212:215]
	v_mfma_f32_16x16x4_f32 v[212:215], v191, v203, v[212:215]
	v_mfma_f32_16x16x4_f32 v[216:219], v192, v200, v[216:219]
	v_mfma_f32_16x16x4_f32 v[216:219], v193, v201, v[216:219]
	v_mfma_f32_16x16x4_f32 v[216:219], v194, v202, v[216:219]
	v_mfma_f32_16x16x4_f32 v[216:219], v195, v203, v[216:219]
	v_mfma_f32_16x16x4_f32 v[220:223], v196, v200, v[220:223]
	v_mfma_f32_16x16x4_f32 v[220:223], v197, v201, v[220:223]
	v_mfma_f32_16x16x4_f32 v[220:223], v198, v202, v[220:223]
	v_mfma_f32_16x16x4_f32 v[220:223], v199, v203, v[220:223]
	v_mfma_f32_16x16x4_f32 v[248:251], v132, v252, v[240:243]
	v_mfma_f32_16x16x4_f32 v[248:251], v133, v253, v[248:251]
	v_mfma_f32_16x16x4_f32 v[248:251], v134, v254, v[248:251]
	v_mfma_f32_16x16x4_f32 v[248:251], v135, v255, v[248:251]
	v_mul_f32_e32 v208, v208, v140
	v_mul_f32_e32 v209, v209, v141
	v_mul_f32_e32 v210, v210, v142
	v_mul_f32_e32 v211, v211, v143
	v_mul_f32_e32 v212, v212, v144
	v_mul_f32_e32 v213, v213, v145
	v_mul_f32_e32 v214, v214, v146
	v_mul_f32_e32 v215, v215, v147
	v_mul_f32_e32 v216, v216, v148
	v_mul_f32_e32 v217, v217, v149
	v_mul_f32_e32 v218, v218, v150
	v_mul_f32_e32 v219, v219, v151
	v_mul_f32_e32 v220, v220, v152
	v_mul_f32_e32 v221, v221, v153
	v_mul_f32_e32 v222, v222, v154
	v_mul_f32_e32 v223, v223, v155
	s_mov_b64 exec, s[98:99]
	ds_write_b32 v231, v248 offset:6144
	ds_write_b32 v231, v249 offset:6400
	ds_write_b32 v231, v250 offset:6656
	ds_write_b32 v231, v251 offset:6912
	s_mov_b64 exec, -1

	.amdhsa_kernel _Z10hybrid_fwd6Params
		.amdhsa_group_segment_fixed_size 20224
		.amdhsa_private_segment_fixed_size 0
		.amdhsa_kernarg_size 480
		.amdhsa_user_sgpr_count 2
		.amdhsa_user_sgpr_dispatch_ptr 0
		.amdhsa_user_sgpr_queue_ptr 0
		.amdhsa_user_sgpr_kernarg_segment_ptr 1
		.amdhsa_user_sgpr_dispatch_id 0
		.amdhsa_user_sgpr_kernarg_preload_length 0
		.amdhsa_user_sgpr_kernarg_preload_offset 0
		.amdhsa_user_sgpr_private_segment_size 0
		.amdhsa_uses_dynamic_stack 0
		.amdhsa_enable_private_segment 0
		.amdhsa_system_sgpr_workgroup_id_x 1
		.amdhsa_system_sgpr_workgroup_id_y 0
		.amdhsa_system_sgpr_workgroup_id_z 0
		.amdhsa_system_sgpr_workgroup_info 0
		.amdhsa_system_vgpr_workitem_id 2
		.amdhsa_next_free_vgpr 256
		.amdhsa_next_free_sgpr 102
		.amdhsa_accum_offset 256
		.amdhsa_reserve_vcc 1
		.amdhsa_float_round_mode_32 0
		.amdhsa_float_round_mode_16_64 0
		.amdhsa_float_denorm_mode_32 3
		.amdhsa_float_denorm_mode_16_64 3
		.amdhsa_dx10_clamp 1
		.amdhsa_ieee_mode 1
		.amdhsa_fp16_overflow 0
		.amdhsa_tg_split 0
		.amdhsa_exception_fp_ieee_invalid_op 0
		.amdhsa_exception_fp_denorm_src 0
		.amdhsa_exception_fp_ieee_div_zero 0
		.amdhsa_exception_fp_ieee_overflow 0
		.amdhsa_exception_fp_ieee_underflow 0
		.amdhsa_exception_fp_ieee_inexact 0
		.amdhsa_exception_int_div_zero 0
	.end_amdhsa_kernel

.Lfunc_end0:
	.size	_Z10hybrid_fwd6Params, .Lfunc_end0-_Z10hybrid_fwd6Params
	.set _Z10hybrid_fwd6Params.num_vgpr, 256
	.set _Z10hybrid_fwd6Params.num_agpr, 0
	.set _Z10hybrid_fwd6Params.numbered_sgpr, 102
	.set _Z10hybrid_fwd6Params.num_named_barrier, 0
	.set _Z10hybrid_fwd6Params.private_seg_size, 0
	.set _Z10hybrid_fwd6Params.uses_vcc, 1
	.set _Z10hybrid_fwd6Params.uses_flat_scratch, 0
	.set _Z10hybrid_fwd6Params.has_dyn_sized_stack, 0
	.set _Z10hybrid_fwd6Params.has_recursion, 0
	.set _Z10hybrid_fwd6Params.has_indirect_call, 0

amdhsa.kernels:
  - .agpr_count:     0
    .args:
      - .offset:         0
        .size:           224
        .value_kind:     by_value
      - .offset:         224
        .size:           4
        .value_kind:     hidden_block_count_x
      - .offset:         228
        .size:           4
        .value_kind:     hidden_block_count_y
      - .offset:         232
        .size:           4
        .value_kind:     hidden_block_count_z
      - .offset:         236
        .size:           2
        .value_kind:     hidden_group_size_x
      - .offset:         238
        .size:           2
        .value_kind:     hidden_group_size_y
      - .offset:         240
        .size:           2
        .value_kind:     hidden_group_size_z
      - .offset:         242
        .size:           2
        .value_kind:     hidden_remainder_x
      - .offset:         244
        .size:           2
        .value_kind:     hidden_remainder_y
      - .offset:         246
        .size:           2
        .value_kind:     hidden_remainder_z
      - .offset:         264
        .size:           8
        .value_kind:     hidden_global_offset_x
      - .offset:         272
        .size:           8
        .value_kind:     hidden_global_offset_y
      - .offset:         280
        .size:           8
        .value_kind:     hidden_global_offset_z
      - .offset:         288
        .size:           2
        .value_kind:     hidden_grid_dims
      - .offset:         312
        .size:           8
        .value_kind:     hidden_multigrid_sync_arg
      - .offset:         344
        .size:           4
        .value_kind:     hidden_dynamic_lds_size
    .group_segment_fixed_size: 20224
    .kernarg_segment_align: 8
    .kernarg_segment_size: 480
    .language:       OpenCL C
    .language_version:
      - 2
      - 0
    .max_flat_workgroup_size: 512
    .name:           _Z10hybrid_fwd6Params
    .private_segment_fixed_size: 0
    .sgpr_count:     108
    .sgpr_spill_count: 0
    .symbol:         _Z10hybrid_fwd6Params.kd
    .uniform_work_group_size: 1
    .uses_dynamic_stack: false
    .vgpr_count:     256
    .vgpr_spill_count: 0
    .wavefront_size: 64
